# padded per-head bias table + ds_read2_b32 in cb64 near path; P4 residual epilogue pair-pipelined (8 x loads in flight)
# baseline (speedup 1.0000x reference)
; #define LAS __attribute__((address_space(3)))
; __device__ __forceinline__ void load_qfrags2(LAS unsigned char* vlds, const bf16_t* q0, int lane, bf16x8 (&qfA)[4], bf16x8 (&qfB)[4]) {
;     asm volatile("" : "+v"(lane));
;     const int r32 = lane & 31, hi = lane >> 5;
;     u32x4 pa[4], pb[4];
; #pragma unroll
;     for (int i = 0; i < 4; ++i) { const int id = lane + 64 * i; const bf16_t* p = q0 + (size_t)(id >> 3) * 512 + (id & 7) * 8; pa[i] = *(const u32x4*)p; pb[i] = *(const u32x4*)(p + 32 * 512); }
;     asm volatile("" ::: "memory");
; #pragma unroll
;     for (int i = 0; i < 4; ++i) { const int id = lane + 64 * i; *(LAS u32x4*)(vlds + 4096 + (id >> 3) * 144 + (id & 7) * 16) = pa[i]; }
;     asm volatile("" ::: "memory");
; #pragma unroll
;     for (int i = 0; i < 4; ++i) qfA[i] = *(const LAS bf16x8*)(vlds + 4096 + r32 * 144 + (2 * i + hi) * 16);
;     asm volatile("" ::: "memory");
; #pragma unroll
;     for (int i = 0; i < 4; ++i) { const int id = lane + 64 * i; *(LAS u32x4*)(vlds + 4096 + (id >> 3) * 144 + (id & 7) * 16) = pb[i]; }
;     asm volatile("" ::: "memory");
; #pragma unroll
;     for (int i = 0; i < 4; ++i) qfB[i] = *(const LAS bf16x8*)(vlds + 4096 + r32 * 144 + (2 * i + hi) * 16);
;     asm volatile("" ::: "memory");
; __device__ __forceinline__ void attn_unit_cb64(const AttnCtx& C, int b, int h, int c, LAS unsigned char* vlds, const LAS float* bias_h, int lane) {
;     const int r32 = lane & 31, hi = lane >> 5;
;     const size_t qrowA = (size_t)b * TT + c * 64 + r32;
;     const int qposA = c * 64 + r32;
;     const int s_hi = c * 64 + 32; int s_lo = (c - 8) * 64; if (s_lo < 0) s_lo = 0;
;     bf16x8 qfA[4], qfB[4];
;     u32x4 kr[4], vr[4];
;     load_tile<false>(C, false, b, h, s_hi, lane, kr, vr);
;     load_qfrags2(vlds, C.QCB + ((size_t)b * TT + c * 64) * 512 + h * 64, lane, qfA, qfB);
;     f32x16 oA0 = {}, oA1 = {}, oB0 = {}, oB1 = {};
;     float mA = -1e30f, lA = 0.f, mB = -1e30f, lB = 0.f;
;     const float bfar = bias_h[256];
;     LAS unsigned char* trb = vlds + (4 * hi + ((lane & 15) >> 2)) * 64 + ((lane >> 4) & 1) * 32 + (lane & 3) * 8;
.LBB0_390:
	s_and_b64 vcc, exec, s[8:9]
	s_cbranch_vccz .LBB0_408
	s_bfe_u32 s17, s81, 0x30006
	s_ashr_i32 s8, s81, 9
	s_mul_i32 s9, s17, 0x404
	s_add_i32 s14, s9, 0
	s_ashr_i32 s9, s8, 31
	s_lshl_b32 s20, s80, 6
	s_lshl_b64 s[10:11], s[8:9], 12
	s_or_b32 s15, s20, 32
	s_or_b32 s12, s10, s20
	s_or_b32 s10, s10, s15
	s_add_i32 s14, s14, 0x14000
	s_mov_b32 s13, s11
	s_lshl_b64 s[10:11], s[10:11], 10
	s_add_u32 s18, s78, s10
	s_addc_u32 s19, s79, s11
	s_lshl_b32 s16, s17, 6
	s_lshl_b32 s17, s17, 7
	s_add_u32 s18, s18, s17
	s_addc_u32 s19, s19, 0
	v_lshlrev_b32_e32 v0, 1, v196
	s_add_u32 s10, s88, s10
	v_lshl_add_u64 v[2:3], s[18:19], 0, v[0:1]
	v_lshlrev_b32_e32 v4, 1, v194
	v_mov_b32_e32 v5, v1
	s_addc_u32 s11, s89, s11
	v_lshl_add_u64 v[6:7], v[2:3], 0, v[4:5]
	v_lshlrev_b32_e32 v8, 1, v198
	v_mov_b32_e32 v9, v1
	v_lshl_add_u64 v[10:11], v[2:3], 0, v[8:9]
	global_load_dwordx4 v[144:147], v[6:7], off
	global_load_dwordx4 v[128:131], v[10:11], off
	v_lshlrev_b32_e32 v6, 1, v200
	v_mov_b32_e32 v7, v1
	v_lshlrev_b32_e32 v12, 1, v202
	v_mov_b32_e32 v13, v1
	s_add_u32 s10, s10, s17
	v_lshl_add_u64 v[10:11], v[2:3], 0, v[6:7]
	v_lshl_add_u64 v[2:3], v[2:3], 0, v[12:13]
	s_addc_u32 s11, s11, 0
	global_load_dwordx4 v[132:135], v[10:11], off
	global_load_dwordx4 v[136:139], v[2:3], off
	v_lshl_add_u64 v[2:3], s[10:11], 0, v[0:1]
	s_lshl_b64 s[10:11], s[12:13], 10
	v_lshl_add_u64 v[4:5], v[2:3], 0, v[4:5]
	s_add_u32 s12, s95, s10
	v_lshl_add_u64 v[8:9], v[2:3], 0, v[8:9]
	global_load_dwordx4 v[140:143], v[4:5], off
	global_load_dwordx4 v[148:151], v[8:9], off
	v_lshl_add_u64 v[4:5], v[2:3], 0, v[6:7]
	s_addc_u32 s13, s96, s11
	v_mov_b32_e32 v42, v192
	v_lshl_add_u64 v[2:3], v[2:3], 0, v[12:13]
	global_load_dwordx4 v[152:155], v[4:5], off
	global_load_dwordx4 v[156:159], v[2:3], off
	s_add_u32 s12, s12, s17
	s_addc_u32 s13, s13, 0
	v_lshlrev_b32_e32 v0, 4, v42
	v_ashrrev_i32_e32 v34, 3, v42
	v_and_b32_e32 v0, 0x70, v0
	v_ashrrev_i32_e32 v35, 31, v34
	v_add_u32_e32 v10, 64, v42
	v_add_u32_e32 v14, 0x80, v42
	v_lshl_add_u64 v[18:19], s[12:13], 0, v[0:1]
	v_lshlrev_b64 v[2:3], 10, v[34:35]
	v_ashrrev_i32_e32 v36, 3, v10
	v_ashrrev_i32_e32 v38, 3, v14
	v_add_u32_e32 v20, 0xc0, v42
	v_lshl_add_u64 v[2:3], v[18:19], 0, v[2:3]
	v_ashrrev_i32_e32 v37, 31, v36
	v_ashrrev_i32_e32 v39, 31, v38
	v_ashrrev_i32_e32 v40, 3, v20
	v_add_co_u32_e32 v6, vcc, s77, v2
	v_lshlrev_b64 v[10:11], 10, v[36:37]
	v_lshlrev_b64 v[14:15], 10, v[38:39]
	v_ashrrev_i32_e32 v41, 31, v40
	v_addc_co_u32_e32 v7, vcc, 0, v3, vcc
	v_lshl_add_u64 v[22:23], v[18:19], 0, v[10:11]
	v_lshl_add_u64 v[26:27], v[18:19], 0, v[14:15]
	v_lshlrev_b64 v[20:21], 10, v[40:41]
	global_load_dwordx4 v[2:5], v[2:3], off
	s_nop 0
	global_load_dwordx4 v[6:9], v[6:7], off
	v_lshl_add_u64 v[30:31], v[18:19], 0, v[20:21]
	global_load_dwordx4 v[10:13], v[22:23], off
	global_load_dwordx4 v[14:17], v[26:27], off
	v_add_co_u32_e32 v22, vcc, s77, v22
	global_load_dwordx4 v[18:21], v[30:31], off
	s_nop 0
	v_addc_co_u32_e32 v23, vcc, 0, v23, vcc
	v_add_co_u32_e32 v26, vcc, s77, v26
	global_load_dwordx4 v[22:25], v[22:23], off
	s_nop 0
	v_addc_co_u32_e32 v27, vcc, 0, v27, vcc
	v_add_co_u32_e32 v30, vcc, s77, v30
	global_load_dwordx4 v[26:29], v[26:27], off
	s_nop 0
	v_addc_co_u32_e32 v31, vcc, 0, v31, vcc
	global_load_dwordx4 v[30:33], v[30:31], off
	v_add_u32_e32 v0, s94, v0
	v_mad_u64_u32 v[34:35], s[12:13], v34, s82, v[0:1]
	v_and_b32_e32 v37, 31, v42
	s_lshl_b64 s[8:9], s[8:9], 22
	v_sub_u32_e64 v230, s20, v245 clamp
	v_mov_b32_e32 v231, 0xf149f2ca
	v_mov_b32_e32 v228, 0
	v_mov_b32_e32 v229, 0
	v_mov_b32_e32 v232, 0xf149f2ca
	s_waitcnt vmcnt(7)
	ds_write_b128 v34, v[2:5] offset:4096
	v_mad_u64_u32 v[2:3], s[12:13], v36, s82, v[0:1]
	s_waitcnt vmcnt(5)
	ds_write_b128 v2, v[10:13] offset:4096
	v_mad_u64_u32 v[4:5], s[12:13], v38, s82, v[0:1]
	v_mad_u64_u32 v[10:11], s[12:13], v40, s82, v[0:1]
	v_ashrrev_i32_e32 v3, 1, v42
	s_waitcnt vmcnt(4)
	ds_write_b128 v4, v[14:17] offset:4096
	s_waitcnt vmcnt(3)
	ds_write_b128 v10, v[18:21] offset:4096
	v_mul_u32_u24_e32 v0, 0x90, v37
	v_and_b32_e32 v3, -16, v3
	v_add3_u32 v0, s94, v0, v3
	ds_read_b128 v[160:163], v0 offset:4096
	ds_read_b128 v[164:167], v0 offset:4128
	ds_read_b128 v[168:171], v0 offset:4160
	ds_read_b128 v[172:175], v0 offset:4192
	ds_write_b128 v34, v[6:9] offset:4096
	s_waitcnt vmcnt(2)
	ds_write_b128 v2, v[22:25] offset:4096
	s_waitcnt vmcnt(1)
	ds_write_b128 v4, v[26:29] offset:4096
	s_waitcnt vmcnt(0)
	ds_write_b128 v10, v[30:33] offset:4096
	ds_read_b128 v[176:179], v0 offset:4096
	ds_read_b128 v[180:183], v0 offset:4128
	ds_read_b128 v[184:187], v0 offset:4160
	ds_read_b128 v[188:191], v0 offset:4192
	v_mov_b32_e32 v0, s14
	ds_read_b32 v222, v0 offset:1024
	s_mul_i32 s14, s16, 20
	s_add_i32 s14, s14, 0x18000
	s_add_i32 s12, s92, s33
	s_and_b32 s12, s12, 63
	s_lshl_b32 s12, s12, 16
	s_or_b32 s8, s8, s12
	v_mov_b32_e32 v14, v1
	v_mov_b32_e32 v15, v1
	s_or_b32 s8, s8, s17
	v_mov_b32_e32 v0, v1
	v_mov_b32_e32 v2, v1
	v_mov_b32_e32 v3, v1
	v_mov_b32_e32 v4, v1
	v_mov_b32_e32 v5, v1
	v_mov_b32_e32 v6, v1
	v_mov_b32_e32 v7, v1
	v_mov_b32_e32 v8, v1
	v_mov_b32_e32 v9, v1
	v_mov_b32_e32 v10, v1
	v_mov_b32_e32 v11, v1
	v_mov_b32_e32 v12, v1
	v_mov_b32_e32 v13, v1
	v_mov_b64_e32 v[30:31], v[14:15]
	v_mov_b64_e32 v[46:47], v[14:15]
	v_mov_b64_e32 v[62:63], v[14:15]
	v_mov_b64_e32 v[78:79], v[14:15]
	s_waitcnt lgkmcnt(0)
	v_mov_b32_e32 v224, v222
	v_mov_b32_e32 v225, v222
	v_lshl_add_u64 v[226:227], v[220:221], 0, s[8:9]
	s_movk_i32 s17, 0xffc1
	v_mov_b64_e32 v[28:29], v[12:13]
	v_mov_b64_e32 v[26:27], v[10:11]
	v_mov_b64_e32 v[24:25], v[8:9]
	v_mov_b64_e32 v[22:23], v[6:7]
	v_mov_b64_e32 v[20:21], v[4:5]
	v_mov_b64_e32 v[18:19], v[2:3]
	v_mov_b64_e32 v[16:17], v[0:1]
	v_mov_b64_e32 v[44:45], v[12:13]
	v_mov_b64_e32 v[42:43], v[10:11]
	v_mov_b64_e32 v[40:41], v[8:9]
	v_mov_b64_e32 v[38:39], v[6:7]
	v_mov_b64_e32 v[36:37], v[4:5]
	v_mov_b64_e32 v[34:35], v[2:3]
	v_mov_b64_e32 v[32:33], v[0:1]
	v_mov_b64_e32 v[60:61], v[12:13]
	v_mov_b64_e32 v[58:59], v[10:11]
	v_mov_b64_e32 v[56:57], v[8:9]
	v_mov_b64_e32 v[54:55], v[6:7]
	v_mov_b64_e32 v[52:53], v[4:5]
	v_mov_b64_e32 v[50:51], v[2:3]
	v_mov_b64_e32 v[48:49], v[0:1]
	v_mov_b64_e32 v[76:77], v[12:13]
	v_mov_b64_e32 v[74:75], v[10:11]
	v_mov_b64_e32 v[72:73], v[8:9]
	v_mov_b64_e32 v[70:71], v[6:7]
	v_mov_b64_e32 v[68:69], v[4:5]
	v_mov_b64_e32 v[66:67], v[2:3]
	v_mov_b64_e32 v[64:65], v[0:1]
	s_branch .LBB0_393
